# RWKV LoRA stage: both MFMA chains fed from one batch of six ds_read_b128 (A fragments read once, second batch round trip and first write turnaround removed), on top of v39
# speedup vs baseline: 1.0073x; 1.0030x over previous
; #define LAS __attribute__((address_space(3)))
; __device__ __forceinline__ float frcp(float x) { return __builtin_amdgcn_rcpf(x); }
; __device__ __forceinline__ float sigmoidf_(float x) { return frcp(1.0f + __expf(-x)); }
; __device__ __forceinline__ void rwkv_chain(LAS unsigned char* lds, int cid, const bf16_t* P0, const float* mu, const float* w0, const float* w2, const float* a0, const float* a2, ...
;     ...
;         { RW_IDS const int mat = wid >> 2, ntile = wid & 3; const LAS bf16_t* Aop = mat ? wdB : adB; const LAS bf16_t* Bop = mat ? w2B : a2B; LAS float* pre = mat ? preW : preA;
; #pragma unroll
;           for (int mt = 0; mt < 2; ++mt) { f32x4 acc = (f32x4){0.f, 0.f, 0.f, 0.f};
; #pragma unroll
;               for (int ks = 0; ks < 2; ++ks) acc = mfma16(ldsfrag(Bop, 72, ntile * 16, ks * 32, fr, fq), ldsfrag(Aop, 72, mt * 16, ks * 32, fr, fq), acc);
;               *(LAS f32x4*)(pre + (mt * 16 + fr) * 64 + ntile * 16 + fq * 4) = acc; } }
;         __syncthreads();
;         { RW_IDS const int tok = tid >> 4, c0 = (tid & 15) * 4; float kkr[4], av[4], kp[4], wv[4]; float ss = 0.f, bon = 0.f;
; #pragma unroll
;           for (int i = 0; i < 4; ++i) { const int c = c0 + i, ix = tok * 64 + c;
;               const float a = sigmoidf_(cst[c] + preA[ix]); const float sg = sigmoidf_(cst[64 + c] + preW[ix]);
;               wv[i] = -0.60653065971f * sg;
;               const float kraw = kS[ix]; kkr[i] = kraw * cst[128 + c]; ss += kkr[i] * kkr[i];
;               kp[i] = kraw * (1.0f + (a - 1.0f) * cst[192 + c]); av[i] = a; bon += rS[ix] * kp[i] * cst[256 + c]; }
;           ss += dppf<0xB1>(ss); bon += dppf<0xB1>(bon); ss += dppf<0x4E>(ss); bon += dppf<0x4E>(bon);
;           ss += dppf<0x141>(ss); bon += dppf<0x141>(bon); ss += dppf<0x140>(ss); bon += dppf<0x140>(bon);
;           const float inv = frcp(fmaxf(__builtin_amdgcn_sqrtf(ss), 1e-12f));
;           f32x4 o_nk, o_b, o_k, o_w;
; #pragma unroll
;           for (int i = 0; i < 4; ++i) { const float kk = kkr[i] * inv; o_nk[i] = -kk; o_b[i] = kk * av[i]; o_k[i] = kp[i]; o_w[i] = wv[i]; }
;           *(LAS f32x4*)(nkS + tok * 64 + c0) = o_nk; *(LAS f32x4*)(bS + tok * 64 + c0) = o_b; *(LAS f32x4*)(kS + tok * 64 + c0) = o_k; *(LAS f32x4*)(wS + tok * 64 + c0) = o_w;
;           if (dir == 0 && (tid & 15) == 0) BONUS[((size_t)b * SEQ + t0 + tok) * 8 + h] = bon; }
.LBB0_512:
	v_mov_b32_e32 v8, v200
	s_nop 0
	v_readfirstlane_b32 s7, v8
	v_and_b32_e32 v20, 15, v8
	s_bfe_u32 s12, s7, 0x20006
	v_and_b32_e32 v24, 48, v8
	s_cmpk_lt_u32 s7, 0x100
	v_lshl_or_b32 v8, s12, 4, v20
	s_cselect_b32 s13, s58, s59
	v_mul_u32_u24_e32 v8, 0x90, v8
	v_add3_u32 v25, s13, v8, v24
	ds_read_b128 v[8:11], v25
	s_cselect_b32 s7, s75, s74
	v_mul_u32_u24_e32 v12, 0x90, v20
	v_add3_u32 v26, s7, v24, v12
	ds_read_b128 v[12:15], v26
	ds_read_b128 v[16:19], v25 offset:64
	v_lshlrev_b32_e32 v27, 8, v20
	ds_read_b128 v[20:23], v26 offset:64
	ds_read_b128 v[114:117], v26 offset:2304
	ds_read_b128 v[118:121], v26 offset:2368
	s_waitcnt lgkmcnt(4)
	v_mfma_f32_16x16x32_bf16 v[122:125], v[8:11], v[12:15], 0
	s_cselect_b32 s7, s77, s78
	s_lshl_b32 s12, s12, 6
	s_add_i32 s12, s12, s7
	s_waitcnt lgkmcnt(2)
	v_mfma_f32_16x16x32_bf16 v[122:125], v[16:19], v[20:23], v[122:125]
	v_add3_u32 v24, s12, v27, v24
	s_waitcnt lgkmcnt(1)
	v_mfma_f32_16x16x32_bf16 v[126:129], v[8:11], v[114:117], 0
	s_waitcnt lgkmcnt(0)
	v_mfma_f32_16x16x32_bf16 v[126:129], v[16:19], v[118:121], v[126:129]
	s_nop 7
	v_mov_b32_e32 v16, v200
	ds_write_b128 v24, v[122:125]
	ds_write_b128 v24, v[126:129] offset:4096
	s_waitcnt lgkmcnt(0)
	s_barrier
	s_nop 0
	v_ashrrev_i32_e32 v8, 4, v16
	v_and_b32_e32 v39, 15, v16
	v_lshlrev_b32_e32 v9, 4, v39
	v_lshlrev_b32_e32 v126, 8, v8
	v_add_u32_e32 v127, 0, v9
	v_or_b32_e32 v9, v126, v9
	v_add_u32_e32 v9, 0, v9
	ds_read_b128 v[10:13], v9 offset:49152
	ds_read_b128 v[22:25], v9 offset:57344
	ds_read_b128 v[26:29], v9
	ds_read_b128 v[118:121], v9 offset:8192
	v_mov_b64_e32 v[14:15], v[232:233]
	v_mov_b64_e32 v[16:17], v[234:235]
	v_mov_b64_e32 v[18:19], v[236:237]
	v_mov_b64_e32 v[20:21], v[238:239]
	v_mov_b64_e32 v[30:31], v[248:249]
	v_mov_b64_e32 v[32:33], v[250:251]
	v_mov_b64_e32 v[114:115], v[244:245]
	v_mov_b64_e32 v[116:117], v[246:247]
	v_mov_b64_e32 v[122:123], v[240:241]
	v_mov_b64_e32 v[124:125], v[242:243]
	s_waitcnt lgkmcnt(3)
	v_add_f32_e32 v10, v14, v10
	v_mul_f32_e32 v10, 0xbfb8aa3b, v10
	s_waitcnt lgkmcnt(2)
	v_add_f32_e32 v14, v18, v22
	v_exp_f32_e32 v10, v10
	v_mul_f32_e32 v14, 0xbfb8aa3b, v14
	v_exp_f32_e32 v14, v14
	v_add_f32_e32 v11, v15, v11
	v_mul_f32_e32 v11, 0xbfb8aa3b, v11
	v_exp_f32_e32 v11, v11
	v_add_f32_e32 v10, 1.0, v10
	v_rcp_f32_e32 v22, v10
	v_add_f32_e32 v10, 1.0, v14
	v_add_f32_e32 v14, v19, v23
	v_mul_f32_e32 v14, 0xbfb8aa3b, v14
	v_exp_f32_e32 v14, v14
	v_rcp_f32_e32 v34, v10
	v_add_f32_e32 v10, 1.0, v11
	v_rcp_f32_e32 v23, v10
	v_add_f32_e32 v10, 1.0, v14
	v_rcp_f32_e32 v35, v10
	v_pk_add_f32 v[10:11], v[22:23], -1.0 op_sel_hi:[1,0]
	v_pk_fma_f32 v[10:11], v[114:115], v[10:11], 1.0 op_sel_hi:[1,1,0]
	s_waitcnt lgkmcnt(0)
	v_pk_mul_f32 v[18:19], v[118:119], v[122:123]
	v_pk_mul_f32 v[14:15], v[118:119], v[10:11]
	v_add_f32_e32 v11, v16, v12
	v_mul_f32_e32 v11, 0xbfb8aa3b, v11
	v_exp_f32_e32 v11, v11
	v_mul_f32_e32 v9, v26, v14
	v_fma_f32 v9, v30, v9, 0
	v_mul_f32_e32 v10, v27, v15
	v_add_f32_e32 v12, v20, v24
	v_fmac_f32_e32 v9, v31, v10
	v_add_f32_e32 v10, 1.0, v11
	v_add_f32_e32 v11, v17, v13
	v_mul_f32_e32 v12, 0xbfb8aa3b, v12
	v_mul_f32_e32 v11, 0xbfb8aa3b, v11
	v_exp_f32_e32 v16, v12
	v_exp_f32_e32 v11, v11
	v_add_f32_e32 v13, v21, v25
	v_mul_f32_e32 v13, 0xbfb8aa3b, v13
	v_rcp_f32_e32 v12, v10
	v_add_f32_e32 v10, 1.0, v16
	v_exp_f32_e32 v16, v13
	v_add_f32_e32 v11, 1.0, v11
	v_rcp_f32_e32 v13, v11
	v_rcp_f32_e32 v26, v10
	v_add_f32_e32 v10, 1.0, v16
	v_rcp_f32_e32 v27, v10
	v_pk_add_f32 v[10:11], v[12:13], -1.0 op_sel_hi:[1,0]
	v_pk_mul_f32 v[20:21], v[120:121], v[124:125]
	v_pk_fma_f32 v[10:11], v[116:117], v[10:11], 1.0 op_sel_hi:[1,1,0]
	v_pk_mul_f32 v[24:25], v[20:21], v[20:21]
	v_pk_mul_f32 v[16:17], v[120:121], v[10:11]
	s_nop 0
	v_mul_f32_e32 v10, v28, v16
	v_fmac_f32_e32 v9, v32, v10
	v_pk_mul_f32 v[10:11], v[18:19], v[18:19]
	s_nop 0
	v_add_f32_e32 v10, v10, v11
	v_add_f32_e32 v10, v10, v24
	v_add_f32_e32 v10, v10, v25
	v_mul_f32_e32 v11, v29, v17
	v_fmac_f32_e32 v9, v33, v11
	v_add_f32_dpp v10, v10, v10 quad_perm:[1,0,3,2] row_mask:0xf bank_mask:0xf bound_ctrl:1
	v_add_u32_e32 v11, v127, v126
	v_add_f32_dpp v9, v9, v9 quad_perm:[1,0,3,2] row_mask:0xf bank_mask:0xf bound_ctrl:1
	v_add_f32_dpp v10, v10, v10 quad_perm:[2,3,0,1] row_mask:0xf bank_mask:0xf bound_ctrl:1
	s_nop 0
	v_add_f32_dpp v9, v9, v9 quad_perm:[2,3,0,1] row_mask:0xf bank_mask:0xf bound_ctrl:1
	v_add_f32_dpp v10, v10, v10 row_half_mirror row_mask:0xf bank_mask:0xf bound_ctrl:1
	s_nop 0
	v_add_f32_dpp v9, v9, v9 row_half_mirror row_mask:0xf bank_mask:0xf bound_ctrl:1
	v_add_f32_dpp v10, v10, v10 row_mirror row_mask:0xf bank_mask:0xf bound_ctrl:1
	v_sqrt_f32_e32 v10, v10
	s_nop 0
	v_max_f32_e32 v10, 0x2b8cbccc, v10
	v_rcp_f32_e32 v24, v10
	s_nop 0
	v_mov_b32_dpp v10, v9 row_mirror row_mask:0xf bank_mask:0xf bound_ctrl:1
	v_pk_mul_f32 v[28:29], v[18:19], v[24:25] op_sel_hi:[1,0]
	v_pk_mul_f32 v[24:25], v[20:21], v[24:25] op_sel_hi:[1,0]
	v_xor_b32_e32 v19, 0x80000000, v29
	v_xor_b32_e32 v18, 0x80000000, v28
	v_xor_b32_e32 v20, 0x80000000, v24
	v_xor_b32_e32 v21, 0x80000000, v25
	v_pk_mul_f32 v[22:23], v[22:23], v[28:29]
	v_pk_mul_f32 v[24:25], v[12:13], v[24:25]
	v_pk_mul_f32 v[28:29], v[26:27], s[34:35] op_sel_hi:[1,0]
	v_pk_mul_f32 v[26:27], v[34:35], s[34:35] op_sel_hi:[1,0]
	ds_write_b128 v11, v[18:21] offset:32768
	ds_write_b128 v11, v[22:25] offset:40960
	ds_write_b128 v11, v[14:17] offset:8192
	ds_write_b128 v11, v[26:29] offset:24576
	v_or_b32_e32 v11, s87, v39
	v_cmp_eq_u32_e32 vcc, 0, v11
	s_and_saveexec_b64 s[12:13], vcc
	s_cbranch_execz .LBB0_514
	s_add_u32 s14, s40, s46
	v_add_f32_e32 v10, v9, v10
	v_ashrrev_i32_e32 v9, 31, v8
	s_addc_u32 s15, s41, s47
	v_lshl_add_u64 v[8:9], s[14:15], 0, v[8:9]
	v_lshlrev_b64 v[8:9], 5, v[8:9]
	v_lshl_add_u64 v[8:9], s[44:45], 0, v[8:9]
	global_store_dword v[8:9], v10, off
